# mixer-B K tile: 16-byte chunks XOR-swizzled by (row & 15) instead of (row & 7): conflict-free under the ds_read_b128 lane groups
# speedup vs baseline: 1.0034x; 1.0034x over previous
; #define LAS __attribute__((address_space(3)))
; __device__ __forceinline__ int v_st(int k, int c) { const int kk = (k & ~0xC) | ((k & 4) << 1) | ((k & 8) >> 1); return ((kk >> 3) * 4 + (c >> 5)) * 512 + ((kk & 7) * 32 + (c & 31)) * 2; }
; __device__ __forceinline__ int v_rd_base(int lane) { return ((lane & 3) << 3) | (((lane >> 2) & 3) << 6) | (((lane >> 4) & 1) << 5) | (((lane >> 5) & 1) << 8); }
; __device__ __forceinline__ void unit(LAS unsigned char* lds, const bf16* __restrict__ PROJ, bf16* __restrict__ MIXED, const float* __restrict__ subln_g, float lam, int R0, int seq, int h, int qb) {
;     ...
;     const int qrow = 128 * qb + 32 * g + r32;
;     const bf16* Qw = PROJ + (size_t)(R0 + qrow) * PW + 3072 + h * 128 + c * 64 + hi * 8;
; #pragma unroll
;     for (int d0 = 0; d0 < 4; ++d0) qr[d0] = *(const bf16x8*)(Qw + d0 * 16);
;     const bf16* Kh = PROJ + (size_t)R0 * PW + 4096 + h * 128; const bf16* Vh = PROJ + (size_t)R0 * PW + 5120 + h * 128;
;     const int sr = tid >> 4, sc = (tid & 15) * 8, vst0 = v_st(sr, sc), vst1 = v_st(32 + sr, sc);
;     const int vb0 = (int)(uintptr_t)V_lds + v_rd_base(lane);
;     const int cb0 = (c * 64 + hi * 8) * 2;
;     const LAS float* tbq = tb + (4095 - qrow + 4 * hi);
;     const int rc0 = -(128 * qb + 32 * g);
;     const float cL = tb[0], cR = tb[8190];
;     struct { bf16x8 vs0, vs1, ks0, ks1; } sr_[2];
; __global__ void __launch_bounds__(512, 2) fwd_mega(Args a) {
;     ...
;             const float s1 = a.in[9][lane] * a.in[10][lane], s2 = a.in[11][lane] * a.in[12][lane];
;             const float lam = __expf(wave_sum(s1)) - __expf(wave_sum(s2)) + 0.2f;
.LBB0_247:
	v_readlane_b32 s4, v253, 0
	v_lshlrev_b32_e32 v0, 2, v190
	v_readlane_b32 s6, v253, 2
	v_readlane_b32 s7, v253, 3
	s_barrier
	v_readlane_b32 s8, v253, 4
	v_readlane_b32 s9, v253, 5
	v_readlane_b32 s10, v253, 6
	v_readlane_b32 s11, v253, 7
	v_readlane_b32 s12, v253, 8
	v_readlane_b32 s13, v253, 9
	global_load_dword v1, v0, s[6:7]
	global_load_dword v2, v0, s[8:9]
	s_nop 0
	global_load_dword v3, v0, s[10:11]
	s_nop 0
	global_load_dword v0, v0, s[12:13]
	v_mbcnt_lo_u32_b32 v4, -1, 0
	v_mbcnt_hi_u32_b32 v4, -1, v4
	v_and_b32_e32 v5, 64, v4
	v_xor_b32_e32 v6, 1, v4
	v_add_u32_e32 v5, 64, v5
	v_cmp_lt_i32_e32 vcc, v6, v5
	v_xor_b32_e32 v7, 2, v4
	v_xor_b32_e32 v8, 4, v4
	v_cndmask_b32_e32 v6, v4, v6, vcc
	v_lshlrev_b32_e32 v192, 2, v6
	v_cmp_lt_i32_e32 vcc, v7, v5
	v_xor_b32_e32 v9, 8, v4
	v_xor_b32_e32 v10, 16, v4
	v_cndmask_b32_e32 v7, v4, v7, vcc
	v_lshlrev_b32_e32 v193, 2, v7
	v_cmp_lt_i32_e32 vcc, v8, v5
	v_xor_b32_e32 v11, 32, v4
	s_cmpk_gt_i32 s2, 0xfff
	s_mov_b32 s7, 0
	v_readlane_b32 s5, v253, 1
	v_readlane_b32 s14, v253, 10
	v_readlane_b32 s15, v253, 11
	v_readlane_b32 s16, v253, 12
	v_readlane_b32 s17, v253, 13
	v_readlane_b32 s18, v253, 14
	v_readlane_b32 s19, v253, 15
	s_waitcnt vmcnt(2)
	v_mul_f32_e32 v6, v1, v2
	ds_bpermute_b32 v6, v192, v6
	s_waitcnt vmcnt(0)
	v_mul_f32_e32 v12, v3, v0
	ds_bpermute_b32 v12, v192, v12
	s_waitcnt lgkmcnt(1)
	v_fmac_f32_e32 v6, v1, v2
	v_cndmask_b32_e32 v2, v4, v8, vcc
	s_waitcnt lgkmcnt(0)
	v_fmac_f32_e32 v12, v3, v0
	ds_bpermute_b32 v0, v193, v6
	ds_bpermute_b32 v1, v193, v12
	v_lshlrev_b32_e32 v194, 2, v2
	v_cmp_lt_i32_e32 vcc, v9, v5
	s_waitcnt lgkmcnt(1)
	v_add_f32_e32 v0, v6, v0
	s_waitcnt lgkmcnt(0)
	v_add_f32_e32 v1, v12, v1
	ds_bpermute_b32 v2, v194, v0
	ds_bpermute_b32 v3, v194, v1
	v_cndmask_b32_e32 v6, v4, v9, vcc
	v_lshlrev_b32_e32 v195, 2, v6
	v_cmp_lt_i32_e32 vcc, v10, v5
	s_waitcnt lgkmcnt(1)
	v_add_f32_e32 v0, v0, v2
	s_waitcnt lgkmcnt(0)
	v_add_f32_e32 v1, v1, v3
	ds_bpermute_b32 v2, v195, v0
	ds_bpermute_b32 v3, v195, v1
	v_cndmask_b32_e32 v6, v4, v10, vcc
	v_lshlrev_b32_e32 v196, 2, v6
	v_cmp_lt_i32_e32 vcc, v11, v5
	s_waitcnt lgkmcnt(1)
	v_add_f32_e32 v0, v0, v2
	s_waitcnt lgkmcnt(0)
	v_add_f32_e32 v2, v1, v3
	ds_bpermute_b32 v1, v196, v0
	ds_bpermute_b32 v3, v196, v2
	v_cndmask_b32_e32 v4, v4, v11, vcc
	v_lshlrev_b32_e32 v4, 2, v4
	s_waitcnt lgkmcnt(1)
	v_add_f32_e32 v1, v0, v1
	s_waitcnt lgkmcnt(0)
	v_add_f32_e32 v0, v2, v3
	ds_bpermute_b32 v3, v4, v1
	ds_bpermute_b32 v2, v4, v0
	s_cbranch_scc1 .LBB0_296
	s_waitcnt lgkmcnt(1)
	v_add_f32_e32 v1, v1, v3
	s_waitcnt lgkmcnt(0)
	v_add_f32_e32 v0, v0, v2
	v_mul_f32_e32 v1, 0x3fb8aa3b, v1
	v_mul_f32_e32 v0, 0x3fb8aa3b, v0
	v_exp_f32_e32 v1, v1
	v_exp_f32_e32 v0, v0
	v_lshrrev_b32_e32 v4, 3, v168
	v_and_b32_e32 v2, 0x78, v191
	v_bfe_u32 v5, v191, 5, 2
	v_sub_f32_e32 v0, v1, v0
	v_lshrrev_b32_e32 v1, 4, v168
	v_add_u32_e32 v8, 32, v1
	v_and_b32_e32 v3, 48, v1
	v_and_b32_e32 v9, 0x70, v8
	v_lshlrev_b32_e32 v10, 1, v8
	v_and_or_b32 v3, v4, 8, v3
	v_and_or_b32 v9, v10, 8, v9
	v_lshrrev_b32_e32 v4, 5, v168
	v_lshrrev_b32_e32 v3, 1, v3
	v_bfe_u32 v6, v168, 4, 2
	v_lshrrev_b32_e32 v9, 1, v9
	v_or_b32_e32 v3, v3, v5
	v_and_or_b32 v4, v4, 4, v6
	v_lshlrev_b32_e32 v6, 1, v2
	v_or_b32_e32 v5, v9, v5
	v_lshlrev_b32_e32 v3, 9, v3
	v_lshlrev_b32_e32 v4, 6, v4
	v_and_b32_e32 v7, 48, v6
	v_lshlrev_b32_e32 v5, 9, v5
	v_readlane_b32 s8, v253, 0
	v_mov_b32_e32 v161, 0
	v_or3_b32 v3, v3, v4, v7
	v_or3_b32 v5, v5, v4, v7
	v_mul_u32_u24_e32 v4, 0x1800, v1
	v_lshlrev_b32_e32 v1, 8, v1
	v_and_b32_e32 v7, 0xf0, v168
	v_lshlrev_b32_e32 v8, 8, v8
	v_lshlrev_b32_e32 v160, 2, v169
	v_readlane_b32 s18, v253, 10
	v_readlane_b32 s19, v253, 11
	v_bitop3_b32 v1, v6, v1, v7 bitop3:0xde
	v_bitop3_b32 v8, v6, v8, v7 bitop3:0xde
	s_add_i32 s4, 0, 0x4000
	v_lshl_add_u64 v[162:163], s[18:19], 0, v[160:161]
	v_add_u32_e32 v6, 0, v198
	v_lshlrev_b32_e32 v160, 4, v168
	v_add_u32_e32 v186, s4, v207
	v_add_u32_e32 v187, 0x10000, v6
	v_lshl_add_u64 v[6:7], s[74:75], 0, v[160:161]
	s_mov_b64 s[4:5], 0x6200000
	v_lshl_add_u64 v[164:165], v[6:7], 0, s[4:5]
	v_lshrrev_b32_e32 v6, 4, v168
	v_mul_hi_u32_u24_e32 v7, 0x3000, v6
	v_mul_u32_u24_e32 v6, 0x3000, v6
	v_and_b32_e32 v9, 15, v168
	v_lshl_or_b32 v6, v9, 4, v6
	v_lshl_add_u64 v[6:7], s[74:75], 0, v[6:7]
	s_mov_b64 s[4:5], 0x16762800
	v_add_f32_e32 v173, 0x3e4ccccd, v0
	v_lshlrev_b32_e32 v0, 3, v178
	v_readlane_b32 s9, v253, 1
	v_readlane_b32 s10, v253, 2
	v_readlane_b32 s11, v253, 3
	v_readlane_b32 s12, v253, 4
	v_readlane_b32 s13, v253, 5
	v_readlane_b32 s14, v253, 6
	v_readlane_b32 s15, v253, 7
	v_readlane_b32 s16, v253, 8
	v_readlane_b32 s17, v253, 9
	v_readlane_b32 s20, v253, 12
	v_readlane_b32 s21, v253, 13
	v_readlane_b32 s22, v253, 14
	v_readlane_b32 s23, v253, 15
	v_lshl_add_u64 v[166:167], v[6:7], 0, s[4:5]
	v_lshl_add_u32 v6, v178, 4, 0
	v_add_u32_e32 v175, 0, v207
	v_and_b32_e32 v184, 0xf0, v198
	v_lshl_add_u32 v185, v169, 8, 0
	v_cmp_gt_u32_e64 s[0:1], 32, v190
	v_add_u32_e32 v188, 0x140fc, v6
	s_mov_b64 s[8:9], 0x2000
	v_lshlrev_b32_e32 v160, 1, v0
	s_add_i32 s30, 0, 0x10000
	s_add_i32 s31, 0, 0x17ff8
	v_lshlrev_b32_e32 v178, 1, v4
	v_lshlrev_b32_e32 v180, 1, v2
	s_mov_b32 s34, 0x60000
	s_mov_b32 s35, 0x41000000
	s_mov_b32 s54, 0xc0000
	s_mov_b32 s55, 0x120000
	s_mov_b32 s56, 0x1e0000
	s_mov_b32 s57, 0x180000
	v_mov_b32_e32 v189, 0x358637bd
	s_mov_b32 s58, 0xf800000
	v_mov_b32_e32 v209, 0x260
	s_movk_i32 s59, 0x7fff
	s_mov_b64 s[10:11], 0x10000
	s_mov_b64 s[12:13], 0x11000
	s_mov_b64 s[14:15], 0x12000
	s_mov_b64 s[16:17], 0x13000
	s_mov_b64 s[18:19], 0x18000
	s_mov_b64 s[20:21], 0x19000
	s_mov_b64 s[22:23], 0x1a000
	s_mov_b64 s[24:25], 0x1b000
	v_add_u32_e32 v210, 0, v3
	v_add_u32_e32 v211, 0, v5
	v_add_u32_e32 v212, 0, v1
	v_add_u32_e32 v213, 0, v8
	v_mov_b32_e32 v214, 0xf149f2ca
	s_mov_b32 s60, s2
	s_branch .LBB0_250
